# v039 + P0 row loop: the wait for the first row load moved below all 16 loads (vmcnt(15)) so the second half of the loads no longer waits for the first load and the previous iteration's stores
# baseline (speedup 1.0000x reference)
; __device__ __forceinline__ float bflo(unsigned u) { return __uint_as_float(u << 16); }
; __device__ __forceinline__ float bfhi(unsigned u) { return __uint_as_float(u & 0xffff0000u); }
; template <bool HASY, bool WRITEH, bool WRITEXN>
; __device__ __forceinline__ void norm_rows(int gw, int ngw, int lane, const float* base, const bf16_t* Y, const float* part, const float* wpost, float alpha,
;                                           float* hout, const float* wpre, bf16_t* XN) {
;     ...
;     for (int m0 = gw * RB; m0 < M; m0 += ngw * RB) {
;         f32x4 v[RB][4]; u32x2 y[RB][4]; float ps[RB];
; #pragma unroll
;         for (int rr = 0; rr < RB; ++rr) {
;             const size_t m = (size_t)(m0 + rr);
; #pragma unroll
;             for (int j = 0; j < 4; ++j) v[rr][j] = __builtin_nontemporal_load(((const f32x4*)(base + m * DM)) + lane + 64 * j);
;             if (HASY) {
; #pragma unroll
;                 for (int j = 0; j < 4; ++j) y[rr][j] = __builtin_nontemporal_load(((const u32x2*)(Y + m * DM)) + lane + 64 * j);
;                 ps[rr] = part[m * 16 + (lane & 15)];
;             }
;         }
; #pragma unroll
;         for (int rr = 0; rr < RB; ++rr) {
;             const size_t m = (size_t)(m0 + rr);
;             if (HASY) {
;                 float p = ps[rr];
;                 p += __shfl_xor(p, 1); p += __shfl_xor(p, 2); p += __shfl_xor(p, 4); p += __shfl_xor(p, 8);
;                 const float r = alpha * rsqrtf(p * (1.0f / DM) + EPS);
; #pragma unroll
;                 for (int j = 0; j < 4; ++j) {
;                     const f32x4 w = ((const f32x4*)wpost)[lane + 64 * j];
;                     v[rr][j][0] += bflo(y[rr][j].x) * r * w[0]; v[rr][j][1] += bfhi(y[rr][j].x) * r * w[1]; v[rr][j][2] += bflo(y[rr][j].y) * r * w[2]; v[rr][j][3] += bfhi(y[rr][j].y) * r * w[3];
;                 }
;             }
;             if (WRITEH) {
; #pragma unroll
;                 for (int j = 0; j < 4; ++j) ((f32x4*)(hout + m * DM))[lane + 64 * j] = v[rr][j];
;             }
;             if (WRITEXN) {
;                 float s2 = 0.f;
; #pragma unroll
;                 for (int j = 0; j < 4; ++j) s2 += (v[rr][j][0] * v[rr][j][0] + v[rr][j][1] * v[rr][j][1]) + (v[rr][j][2] * v[rr][j][2] + v[rr][j][3] * v[rr][j][3]);
;                 s2 = wave_sum(s2);
;                 if (lane < 16) hout[m * 16 + lane] = (lane == 0) ? s2 : 0.f;
.LBB0_79:
	v_add_co_u32_e32 v0, vcc, 0xffffd000, v68
	s_nop 1
	v_addc_co_u32_e32 v1, vcc, -1, v69, vcc
	global_load_dwordx4 v[60:63], v[0:1], off offset:-3072 nt
	global_load_dwordx4 v[56:59], v[0:1], off offset:-2048 nt
	global_load_dwordx4 v[52:55], v[0:1], off offset:-1024 nt
	global_load_dwordx4 v[48:51], v[0:1], off nt
	global_load_dwordx4 v[12:15], v[68:69], off offset:-3072 nt
	global_load_dwordx4 v[8:11], v[68:69], off offset:-2048 nt
	global_load_dwordx4 v[4:7], v[68:69], off offset:-1024 nt
	s_nop 0
	global_load_dwordx4 v[0:3], v[68:69], off nt
	v_add_co_u32_e32 v16, vcc, 0xffffe000, v68
	s_nop 1
	v_addc_co_u32_e32 v17, vcc, -1, v69, vcc
	v_add_co_u32_e32 v18, vcc, 0xfffff000, v68
	global_load_dwordx4 v[44:47], v[16:17], off offset:-3072 nt
	global_load_dwordx4 v[40:43], v[16:17], off offset:-2048 nt
	global_load_dwordx4 v[36:39], v[16:17], off offset:-1024 nt
	global_load_dwordx4 v[32:35], v[16:17], off nt
	v_addc_co_u32_e32 v19, vcc, -1, v69, vcc
	global_load_dwordx4 v[28:31], v[18:19], off offset:-3072 nt
	global_load_dwordx4 v[24:27], v[18:19], off offset:-2048 nt
	s_waitcnt lgkmcnt(0)
	global_load_dwordx4 v[20:23], v[18:19], off offset:-1024 nt
	s_nop 0
	global_load_dwordx4 v[16:19], v[68:69], off offset:-4096 nt
	s_waitcnt vmcnt(15)
	v_mul_f32_e32 v70, v61, v61
	v_mul_f32_e32 v71, v63, v63
	s_waitcnt vmcnt(14)
	v_mul_f32_e32 v78, v57, v57
	v_mul_f32_e32 v79, v59, v59
	s_waitcnt vmcnt(13)
	v_mul_f32_e32 v80, v53, v53
	v_mul_f32_e32 v81, v55, v55
	v_fmac_f32_e32 v70, v60, v60
	v_fmac_f32_e32 v71, v62, v62
	v_fmac_f32_e32 v78, v56, v56
	v_fmac_f32_e32 v79, v58, v58
	s_waitcnt vmcnt(12)
	v_mul_f32_e32 v82, v49, v49
	v_mul_f32_e32 v83, v51, v51
	v_fmac_f32_e32 v80, v52, v52
	v_fmac_f32_e32 v81, v54, v54
	v_add_f32_e32 v70, v70, v71
	v_add_f32_e32 v71, v78, v79
	v_fmac_f32_e32 v82, v48, v48
	v_fmac_f32_e32 v83, v50, v50
	v_add_f32_e32 v78, v80, v81
	v_add_f32_e32 v70, v70, v71
	v_add_f32_e32 v70, v70, v78
	v_add_f32_e32 v71, v82, v83
	v_add_f32_e32 v70, v70, v71
	ds_bpermute_b32 v71, v72, v70
	s_waitcnt lgkmcnt(0)
	v_add_f32_e32 v70, v70, v71
	ds_bpermute_b32 v71, v73, v70
	s_waitcnt lgkmcnt(0)
	v_add_f32_e32 v70, v70, v71
	ds_bpermute_b32 v71, v74, v70
	s_waitcnt lgkmcnt(0)
	v_add_f32_e32 v70, v70, v71
	ds_bpermute_b32 v71, v75, v70
	s_waitcnt lgkmcnt(0)
	v_add_f32_e32 v70, v70, v71
	ds_bpermute_b32 v71, v76, v70
	s_waitcnt lgkmcnt(0)
	v_add_f32_e32 v78, v70, v71
	ds_bpermute_b32 v79, v77, v78
	v_lshl_add_u64 v[70:71], s[64:65], 0, v[64:65]
	s_and_saveexec_b64 s[22:23], s[6:7]
	s_cbranch_execz .LBB0_81
	s_waitcnt lgkmcnt(0)
	v_add_f32_e32 v78, v78, v79
	v_cndmask_b32_e64 v80, 0, v78, s[4:5]
	v_add_co_u32_e32 v78, vcc, 0x2d00000, v70
	s_nop 1
	v_addc_co_u32_e32 v79, vcc, 0, v71, vcc
	global_store_dword v[78:79], v80, off
